# v34: MLA reference-max subtraction folded into the QK MFMA C operand (-m tuple in v160-175, parked consts in LDS); rescale path re-derived and stress-tested at threshold 0; P0 silu loop unrolled
# speedup vs baseline: 1.0109x; 1.0060x over previous
.LBB0_6:
	s_mov_b64 s[4:5], 0x1000
	global_load_dword v10, v[4:5], off
	global_load_dword v11, v[4:5], off offset:2048
	v_lshl_add_u64 v[6:7], v[4:5], 0, s[4:5]
	global_load_dword v12, v[6:7], off
	global_load_dword v13, v[6:7], off offset:2048
	v_lshl_add_u64 v[8:9], v[6:7], 0, s[4:5]
	global_load_dword v14, v[8:9], off
	global_load_dword v15, v[8:9], off offset:2048
	v_lshl_add_u64 v[6:7], v[8:9], 0, s[4:5]
	global_load_dword v16, v[6:7], off
	global_load_dword v17, v[6:7], off offset:2048
	global_load_dword v18, v130, s[62:63]
	global_load_dword v19, v130, s[62:63] offset:2048
	s_waitcnt vmcnt(9)
	v_mul_f32_e32 v8, 0xbfb8aa3b, v10
	v_exp_f32_e32 v8, v8
	s_nop 0
	v_add_f32_e32 v8, 1.0, v8
	v_rcp_f32_e32 v8, v8
	s_nop 0
	v_mul_f32_e32 v10, v10, v8
	ds_write_b32 v1, v10
	s_waitcnt vmcnt(8)
	v_mul_f32_e32 v8, 0xbfb8aa3b, v11
	v_exp_f32_e32 v8, v8
	s_nop 0
	v_add_f32_e32 v8, 1.0, v8
	v_rcp_f32_e32 v8, v8
	s_nop 0
	v_mul_f32_e32 v11, v11, v8
	ds_write_b32 v1, v11 offset:2048
	s_waitcnt vmcnt(7)
	v_mul_f32_e32 v8, 0xbfb8aa3b, v12
	v_exp_f32_e32 v8, v8
	s_nop 0
	v_add_f32_e32 v8, 1.0, v8
	v_rcp_f32_e32 v8, v8
	s_nop 0
	v_mul_f32_e32 v12, v12, v8
	ds_write_b32 v1, v12 offset:4096
	s_waitcnt vmcnt(6)
	v_mul_f32_e32 v8, 0xbfb8aa3b, v13
	v_exp_f32_e32 v8, v8
	s_nop 0
	v_add_f32_e32 v8, 1.0, v8
	v_rcp_f32_e32 v8, v8
	s_nop 0
	v_mul_f32_e32 v13, v13, v8
	ds_write_b32 v1, v13 offset:6144
	s_waitcnt vmcnt(5)
	v_mul_f32_e32 v8, 0xbfb8aa3b, v14
	v_exp_f32_e32 v8, v8
	s_nop 0
	v_add_f32_e32 v8, 1.0, v8
	v_rcp_f32_e32 v8, v8
	s_nop 0
	v_mul_f32_e32 v14, v14, v8
	ds_write_b32 v1, v14 offset:8192
	s_waitcnt vmcnt(4)
	v_mul_f32_e32 v8, 0xbfb8aa3b, v15
	v_exp_f32_e32 v8, v8
	s_nop 0
	v_add_f32_e32 v8, 1.0, v8
	v_rcp_f32_e32 v8, v8
	s_nop 0
	v_mul_f32_e32 v15, v15, v8
	ds_write_b32 v1, v15 offset:10240
	s_waitcnt vmcnt(3)
	v_mul_f32_e32 v8, 0xbfb8aa3b, v16
	v_exp_f32_e32 v8, v8
	s_nop 0
	v_add_f32_e32 v8, 1.0, v8
	v_rcp_f32_e32 v8, v8
	s_nop 0
	v_mul_f32_e32 v16, v16, v8
	ds_write_b32 v1, v16 offset:12288
	s_waitcnt vmcnt(2)
	v_mul_f32_e32 v8, 0xbfb8aa3b, v17
	v_exp_f32_e32 v8, v8
	s_nop 0
	v_add_f32_e32 v8, 1.0, v8
	v_rcp_f32_e32 v8, v8
	s_nop 0
	v_mul_f32_e32 v17, v17, v8
	ds_write_b32 v1, v17 offset:14336
	s_waitcnt vmcnt(1)
	v_mul_f32_e32 v8, 0xbfb8aa3b, v18
	v_exp_f32_e32 v8, v8
	s_nop 0
	v_add_f32_e32 v8, 1.0, v8
	v_rcp_f32_e32 v8, v8
	s_nop 0
	v_mul_f32_e32 v18, v18, v8
	ds_write_b32 v1, v18 offset:16384
	s_waitcnt vmcnt(0)
	v_mul_f32_e32 v8, 0xbfb8aa3b, v19
	v_exp_f32_e32 v8, v8
	s_nop 0
	v_add_f32_e32 v8, 1.0, v8
	v_rcp_f32_e32 v8, v8
	s_nop 0
	v_mul_f32_e32 v19, v19, v8
	ds_write_b32 v1, v19 offset:18432
	s_or_b64 exec, exec, s[0:1]
	s_cmpk_lt_i32 s3, 0x180
	s_cselect_b64 s[0:1], -1, 0
	v_and_b32_e32 v148, 63, v146
	v_writelane_b32 v254, s0, 23
	v_lshrrev_b32_e32 v158, 6, v146
	s_cmpk_gt_i32 s3, 0x17f
	v_writelane_b32 v254, s1, 24
	v_lshlrev_b32_e32 v144, 2, v148
	s_waitcnt lgkmcnt(0)
	s_barrier
	s_cbranch_scc1 .LBB0_14
	v_lshrrev_b32_e32 v4, 6, v146
	v_mul_hi_u32_u24_e32 v5, 0x300000, v4
	v_mul_u32_u24_e32 v4, 0x300000, v4
	s_movk_i32 s0, 0x140
	v_mul_u32_u24_e32 v1, 0x140, v158
	v_lshlrev_b32_e32 v2, 8, v158
	v_or_b32_e32 v4, v4, v144
	v_mov_b32_e32 v3, 0
	v_lshl_or_b32 v1, v1, 2, v144
	v_cmp_gt_u32_e32 vcc, s0, v146
	v_lshl_add_u64 v[4:5], s[64:65], 0, v[4:5]
	v_lshlrev_b32_e32 v12, 9, v158
	s_movk_i32 s2, 0x6000
	s_mov_b32 s8, 0xc000
	s_mov_b32 s9, 0x12000
	s_mov_b32 s10, 0x18000
	s_mov_b32 s11, 0x1e000
	s_mov_b32 s12, 0x24000
	s_mov_b32 s13, 0x2a000
	v_add_u32_e32 v13, v144, v2
	v_lshlrev_b32_e32 v2, 2, v148
	s_mov_b32 s14, s3
	s_branch .LBB0_10

.Lmla_prio_done:
	v_and_b32_e32 v4, 31, v146
	v_lshrrev_b32_e32 v0, 1, v146
	s_movk_i32 s2, 0x1e0
	v_and_or_b32 v153, v0, s2, v4
	v_add_u32_e32 v5, 0x200, v146
	s_movk_i32 s2, 0x100
	v_cmp_gt_u32_e64 s[10:11], s2, v146
	v_mul_u32_u24_e32 v7, 0x1556, v146
	v_mul_u32_u24_e32 v9, 0x1556, v5
	s_mov_b32 s2, 0x7060302
	v_lshrrev_b32_e32 v8, 16, v7
	v_lshrrev_b32_e32 v10, 16, v9
	v_perm_b32 v7, v9, v7, s2
	s_movk_i32 s4, 0x68
	v_mad_i32_i24 v5, v10, -12, v5
	v_pk_mul_lo_u16 v7, v7, s4 op_sel_hi:[1,0]
	v_bfe_u32 v1, v146, 5, 1
	v_and_b32_e32 v6, 56, v147
	v_lshlrev_b32_e32 v142, 3, v5
	v_lshrrev_b32_e32 v180, 16, v7
	v_lshlrev_b32_e32 v5, 4, v5
	v_lshlrev_b32_e32 v0, 3, v1
	v_lshl_add_u32 v181, v180, 1, v5
	v_lshlrev_b32_e32 v158, 1, v6
	v_mul_u32_u24_e32 v5, 0x68, v4
	v_lshlrev_b32_e32 v6, 4, v1
	v_lshlrev_b32_e32 v253, 2, v1
	v_mbcnt_hi_u32_b32 v1, -1, v145
	v_lshl_add_u32 v184, v5, 1, v6
	v_and_b32_e32 v5, 64, v1
	v_mov_b32_e32 v97, 0
	v_mul_u32_u24_e32 v96, 0x4200, v154
	v_mad_i32_i24 v9, v8, -12, v146
	v_mul_u32_u24_e32 v185, 0x48, v4
	v_xor_b32_e32 v4, 32, v1
	v_add_u32_e32 v5, 64, v5
	v_lshl_add_u64 v[2:3], s[12:13], 0, v[96:97]
	v_lshlrev_b32_e32 v138, 3, v9
	v_ashrrev_i32_e32 v143, 31, v142
	v_cmp_lt_i32_e32 vcc, v4, v5
	v_mov_b32_e32 v159, v97
	s_movk_i32 s2, 0xc00
	v_ashrrev_i32_e32 v139, 31, v138
	v_cndmask_b32_e32 v1, v1, v4, vcc
	v_lshl_add_u64 v[162:163], v[2:3], 0, v[158:159]
	v_lshlrev_b64 v[2:3], 1, v[142:143]
	v_and_b32_e32 v11, 0xfff8, v7
	v_lshlrev_b32_e32 v9, 4, v9
	v_mul_u32_u24_e32 v182, 0x48, v154
	v_lshlrev_b32_e32 v186, 2, v1
	v_and_b32_e32 v1, 7, v146
	v_mad_u64_u32 v[166:167], s[4:5], v10, s2, v[2:3]
	v_lshlrev_b64 v[2:3], 1, v[138:139]
	v_mul_hi_u32_u24_e32 v137, 0xc00, v8
	v_mul_u32_u24_e32 v136, 0xc00, v8
	v_mul_u32_u24_e32 v140, 0xc00, v10
	v_mov_b32_e32 v141, v97
	v_lshl_add_u32 v161, v11, 1, v9
	v_lshl_add_u32 v183, v182, 1, v158
	s_mov_b32 s39, 0
	v_lshl_or_b32 v159, v185, 1, v0
	v_lshl_or_b32 v164, v1, 4, v96
	v_mov_b32_e32 v165, v97
	v_mad_u64_u32 v[168:169], s[4:5], v8, s2, v[2:3]
	v_mov_b32_e32 v187, 0x2100
	v_mov_b64_e32 v[170:171], s[94:95]
	v_lshlrev_b32_e32 v172, 1, v0
	v_mov_b32_e32 v173, v97
	v_mov_b32_e32 v188, 0x108000
	v_mov_b32_e32 v189, 0xc0
	s_mov_b64 s[40:41], 0x100
	s_mov_b64 s[42:43], 0x60000
	v_lshlrev_b32_e32 v190, 1, v11
	s_mov_b32 s6, s3
	v_mov_b32_e32 v252, 0x12000
	v_lshl_add_u32 v252, v146, 6, v252
	s_branch .LBB0_2694
.LBB0_2693:
	ds_read_b128 v[160:163], v252
	ds_read_b128 v[164:167], v252 offset:16
	ds_read_b128 v[168:171], v252 offset:32
	ds_read_b128 v[172:175], v252 offset:48
	s_waitcnt lgkmcnt(0)
	ds_bpermute_b32 v34, v186, v192
	v_lshlrev_b64 v[32:33], 11, v[174:175]
	s_lshl_b32 s38, s7, 7
	v_lshl_add_u64 v[32:33], s[96:97], 0, v[32:33]
	v_lshl_add_u64 v[32:33], v[32:33], 0, s[38:39]
	s_waitcnt lgkmcnt(0)
	v_add_f32_e32 v34, v192, v34
	v_div_scale_f32 v35, s[4:5], v34, v34, 1.0
	v_rcp_f32_e32 v36, v35
	v_div_scale_f32 v37, vcc, 1.0, v34, 1.0
	v_lshl_add_u64 v[32:33], v[32:33], 0, v[96:97]
	v_fma_f32 v38, -v35, v36, 1.0
	v_fmac_f32_e32 v36, v38, v36
	v_mul_f32_e32 v38, v37, v36
	v_fma_f32 v39, -v35, v38, v37
	v_fmac_f32_e32 v38, v39, v36
	v_fma_f32 v35, -v35, v38, v37
	v_div_fmas_f32 v35, v35, v36, v38
	v_div_fixup_f32 v34, v35, v34, 1.0
	v_pk_mul_f32 v[16:17], v[16:17], v[34:35] op_sel_hi:[1,0]
	v_pk_mul_f32 v[18:19], v[18:19], v[34:35] op_sel_hi:[1,0]
	v_pk_mul_f32 v[0:1], v[0:1], v[34:35] op_sel_hi:[1,0]
	v_pk_mul_f32 v[2:3], v[2:3], v[34:35] op_sel_hi:[1,0]
	v_cvt_pk_bf16_f32 v16, v16, v17
	v_cvt_pk_bf16_f32 v17, v18, v19
	v_cvt_pk_bf16_f32 v0, v0, v1
	v_cvt_pk_bf16_f32 v1, v2, v3
	global_store_dwordx2 v[32:33], v[16:17], off
	v_pk_mul_f32 v[16:17], v[20:21], v[34:35] op_sel_hi:[1,0]
	v_pk_mul_f32 v[18:19], v[22:23], v[34:35] op_sel_hi:[1,0]
	global_store_dwordx2 v[32:33], v[0:1], off offset:64
	v_pk_mul_f32 v[0:1], v[4:5], v[34:35] op_sel_hi:[1,0]
	v_pk_mul_f32 v[2:3], v[6:7], v[34:35] op_sel_hi:[1,0]
	v_cvt_pk_bf16_f32 v16, v16, v17
	v_cvt_pk_bf16_f32 v17, v18, v19
	v_cvt_pk_bf16_f32 v0, v0, v1
	v_cvt_pk_bf16_f32 v1, v2, v3
	global_store_dwordx2 v[32:33], v[16:17], off offset:16
	v_pk_mul_f32 v[16:17], v[24:25], v[34:35] op_sel_hi:[1,0]
	v_pk_mul_f32 v[18:19], v[26:27], v[34:35] op_sel_hi:[1,0]
	global_store_dwordx2 v[32:33], v[0:1], off offset:80
	v_pk_mul_f32 v[0:1], v[8:9], v[34:35] op_sel_hi:[1,0]
	v_pk_mul_f32 v[2:3], v[10:11], v[34:35] op_sel_hi:[1,0]
	v_cvt_pk_bf16_f32 v16, v16, v17
	v_cvt_pk_bf16_f32 v17, v18, v19
	v_cvt_pk_bf16_f32 v0, v0, v1
	v_cvt_pk_bf16_f32 v1, v2, v3
	global_store_dwordx2 v[32:33], v[16:17], off offset:32
	v_pk_mul_f32 v[16:17], v[28:29], v[34:35] op_sel_hi:[1,0]
	v_pk_mul_f32 v[18:19], v[30:31], v[34:35] op_sel_hi:[1,0]
	global_store_dwordx2 v[32:33], v[0:1], off offset:96
	v_pk_mul_f32 v[0:1], v[12:13], v[34:35] op_sel_hi:[1,0]
	v_pk_mul_f32 v[2:3], v[14:15], v[34:35] op_sel_hi:[1,0]
	s_add_i32 s6, s6, s82
	v_cvt_pk_bf16_f32 v16, v16, v17
	v_cvt_pk_bf16_f32 v17, v18, v19
	v_cvt_pk_bf16_f32 v0, v0, v1
	v_cvt_pk_bf16_f32 v1, v2, v3
	s_cmpk_gt_i32 s6, 0x83f
	global_store_dwordx2 v[32:33], v[16:17], off offset:48
	global_store_dwordx2 v[32:33], v[0:1], off offset:112
	s_cbranch_scc1 .LBB0_2732

.LBB0_2709:
	s_or_b64 exec, exec, s[4:5]
	global_load_dwordx4 v[132:135], v[10:11], off offset:256
	s_waitcnt lgkmcnt(0)
	s_barrier
	ds_read_b128 v[0:3], v184
	ds_read_b128 v[4:7], v184 offset:32
	s_waitcnt lgkmcnt(1)
	v_mfma_f32_32x32x16_bf16 v[48:63], v[0:3], v[100:103], 0
	s_mov_b32 s12, 0
	s_mov_b32 s13, s12
	s_mul_hi_i32 s5, s9, 0x108000
	s_mul_i32 s4, s9, 0x108000
	s_mov_b32 s14, s12
	s_mov_b32 s15, s12
	s_mov_b32 s16, s12
	s_waitcnt lgkmcnt(0)
	v_mfma_f32_32x32x16_bf16 v[48:63], v[4:7], v[104:107], v[48:63]
	ds_read_b128 v[0:3], v184 offset:64
	ds_read_b128 v[4:7], v184 offset:96
	s_mov_b32 s17, s12
	s_mov_b32 s18, s12
	s_mov_b32 s19, s12
	s_mov_b32 s20, s12
	s_mov_b32 s21, s12
	s_mov_b32 s22, s12
	s_waitcnt lgkmcnt(1)
	v_mfma_f32_32x32x16_bf16 v[48:63], v[0:3], v[108:111], v[48:63]
	s_mov_b32 s23, s12
	s_mov_b32 s24, s12
	s_mov_b32 s25, s12
	s_mov_b32 s26, s12
	s_mov_b32 s27, s12
	v_lshl_add_u64 v[98:99], v[164:165], 0, s[4:5]
	s_add_i32 s9, s8, -3
	s_waitcnt lgkmcnt(0)
	v_mfma_f32_32x32x16_bf16 v[48:63], v[4:7], v[112:115], v[48:63]
	ds_read_b128 v[0:3], v184 offset:128
	ds_read_b128 v[4:7], v184 offset:160
	ds_read_b128 v[20:23], v184 offset:6784
	ds_read_b128 v[64:67], v184 offset:6816
	v_mov_b32_e32 v191, 0xf149f2ca
	v_mov_b32_e32 v192, 0
	ds_read_b128 v[16:19], v184 offset:6752
	s_waitcnt lgkmcnt(4)
	v_mfma_f32_32x32x16_bf16 v[48:63], v[0:3], v[116:119], v[48:63]
	ds_read_b128 v[0:3], v184 offset:6656
	s_waitcnt lgkmcnt(4)
	v_mfma_f32_32x32x16_bf16 v[48:63], v[4:7], v[120:123], v[48:63]
	ds_read_b128 v[4:7], v184 offset:6688
	s_waitcnt lgkmcnt(1)
	v_mfma_f32_32x32x16_bf16 v[32:47], v[0:3], v[100:103], 0
	ds_read_b128 v[0:3], v184 offset:6720
	s_waitcnt lgkmcnt(1)
	v_mfma_f32_32x32x16_bf16 v[32:47], v[4:7], v[104:107], v[32:47]
	s_waitcnt lgkmcnt(0)
	v_mfma_f32_32x32x16_bf16 v[32:47], v[0:3], v[108:111], v[32:47]
	v_mov_b64_e32 v[0:1], s[12:13]
	v_mov_b64_e32 v[14:15], s[26:27]
	v_mov_b64_e32 v[2:3], s[14:15]
	v_mov_b64_e32 v[4:5], s[16:17]
	v_mov_b64_e32 v[6:7], s[18:19]
	v_mov_b64_e32 v[8:9], s[20:21]
	v_mov_b64_e32 v[10:11], s[22:23]
	v_mfma_f32_32x32x16_bf16 v[32:47], v[16:19], v[112:115], v[32:47]
	v_lshl_add_u64 v[16:17], v[166:167], 0, s[44:45]
	v_mad_u64_u32 v[176:177], s[4:5], s7, v189, v[16:17]
	v_lshl_add_u64 v[16:17], v[168:169], 0, s[44:45]
	v_mov_b64_e32 v[12:13], s[24:25]
	v_mad_u64_u32 v[178:179], s[4:5], s7, v189, v[16:17]
	v_mfma_f32_32x32x16_bf16 v[32:47], v[20:23], v[116:119], v[32:47]
	v_mov_b64_e32 v[30:31], v[14:15]
	s_mov_b32 s13, 1
	s_mov_b32 s4, 2
	s_mov_b32 s16, 4
	v_mov_b64_e32 v[28:29], v[12:13]
	v_mov_b64_e32 v[26:27], v[10:11]
	v_mov_b64_e32 v[24:25], v[8:9]
	v_mfma_f32_32x32x16_bf16 v[32:47], v[64:67], v[120:123], v[32:47]
	v_mov_b64_e32 v[22:23], v[6:7]
	v_mov_b64_e32 v[20:21], v[4:5]
	v_mov_b64_e32 v[18:19], v[2:3]
	v_mov_b64_e32 v[16:17], v[0:1]
	ds_write_b128 v252, v[160:163]
	ds_write_b128 v252, v[164:167] offset:16
	ds_write_b128 v252, v[168:171] offset:32
	ds_write_b128 v252, v[172:175] offset:48
	s_nop 7
	s_nop 7
	v_max_f32_e32 v96, v48, v49
	v_max3_f32 v96, v96, v50, v51
	v_max3_f32 v96, v96, v52, v53
	v_max3_f32 v96, v96, v54, v55
	v_max3_f32 v96, v96, v56, v57
	v_max3_f32 v96, v96, v58, v59
	v_max3_f32 v96, v96, v60, v61
	v_max3_f32 v96, v96, v62, v63
	v_max3_f32 v96, v96, v32, v33
	v_max3_f32 v96, v96, v34, v35
	v_max3_f32 v96, v96, v36, v37
	v_max3_f32 v96, v96, v38, v39
	v_max3_f32 v96, v96, v40, v41
	v_max3_f32 v96, v96, v42, v43
	v_max3_f32 v96, v96, v44, v45
	v_max3_f32 v96, v96, v46, v47
	s_nop 1
	ds_bpermute_b32 v193, v186, v96
	s_waitcnt lgkmcnt(0)
	v_max_f32_e32 v96, v96, v193
	v_sub_f32_e32 v160, 0, v96
	v_sub_f32_e32 v161, 0, v96
	v_sub_f32_e32 v162, 0, v96
	v_sub_f32_e32 v163, 0, v96
	v_sub_f32_e32 v164, 0, v96
	v_sub_f32_e32 v165, 0, v96
	v_sub_f32_e32 v166, 0, v96
	v_sub_f32_e32 v167, 0, v96
	v_sub_f32_e32 v168, 0, v96
	v_sub_f32_e32 v169, 0, v96
	v_sub_f32_e32 v170, 0, v96
	v_sub_f32_e32 v171, 0, v96
	v_sub_f32_e32 v172, 0, v96
	v_sub_f32_e32 v173, 0, v96
	v_sub_f32_e32 v174, 0, v96
	v_sub_f32_e32 v175, 0, v96
	v_sub_f32_e32 v48, v48, v96
	v_sub_f32_e32 v49, v49, v96
	v_sub_f32_e32 v50, v50, v96
	v_sub_f32_e32 v51, v51, v96
	v_sub_f32_e32 v52, v52, v96
	v_sub_f32_e32 v53, v53, v96
	v_sub_f32_e32 v54, v54, v96
	v_sub_f32_e32 v55, v55, v96
	v_sub_f32_e32 v56, v56, v96
	v_sub_f32_e32 v57, v57, v96
	v_sub_f32_e32 v58, v58, v96
	v_sub_f32_e32 v59, v59, v96
	v_sub_f32_e32 v60, v60, v96
	v_sub_f32_e32 v61, v61, v96
	v_sub_f32_e32 v62, v62, v96
	v_sub_f32_e32 v63, v63, v96
	v_sub_f32_e32 v32, v32, v96
	v_sub_f32_e32 v33, v33, v96
	v_sub_f32_e32 v34, v34, v96
	v_sub_f32_e32 v35, v35, v96
	v_sub_f32_e32 v36, v36, v96
	v_sub_f32_e32 v37, v37, v96
	v_sub_f32_e32 v38, v38, v96
	v_sub_f32_e32 v39, v39, v96
	v_sub_f32_e32 v40, v40, v96
	v_sub_f32_e32 v41, v41, v96
	v_sub_f32_e32 v42, v42, v96
	v_sub_f32_e32 v43, v43, v96
	v_sub_f32_e32 v44, v44, v96
	v_sub_f32_e32 v45, v45, v96
	v_sub_f32_e32 v46, v46, v96
	v_sub_f32_e32 v47, v47, v96

.LBB0_2717:
	s_mul_i32 s4, s13, 0x3400
	v_add_u32_e32 v227, s4, v184
	ds_read_b128 v[236:239], v227
	ds_read_b128 v[240:243], v227 offset:32
	ds_read_b128 v[244:247], v227 offset:64
	ds_read_b128 v[248:251], v227 offset:96
	ds_read_b128 v[228:231], v227 offset:128
	ds_read_b128 v[232:235], v227 offset:160
	v_max_f32_e32 v193, v48, v48
	v_max_f32_e32 v96, v49, v49
	v_max_f32_e32 v96, v193, v96
	v_max3_f32 v96, v96, v50, v51
	v_max3_f32 v96, v96, v52, v53
	v_max3_f32 v96, v96, v54, v55
	s_waitcnt lgkmcnt(5)
	v_mfma_f32_32x32x16_bf16 v[80:95], v[236:239], v[100:103], v[160:175]
	ds_read_b128 v[236:239], v227 offset:6656
	v_max3_f32 v96, v96, v56, v57
	v_max3_f32 v96, v96, v58, v59
	v_max3_f32 v96, v96, v60, v61
	v_max3_f32 v96, v96, v62, v63
	s_waitcnt lgkmcnt(5)
	v_mfma_f32_32x32x16_bf16 v[80:95], v[240:243], v[104:107], v[80:95]
	ds_read_b128 v[240:243], v227 offset:6688
	v_max3_f32 v96, v96, v32, v33
	v_max3_f32 v96, v96, v34, v35
	v_max3_f32 v96, v96, v36, v37
	v_max3_f32 v96, v96, v38, v39
	s_waitcnt lgkmcnt(5)
	v_mfma_f32_32x32x16_bf16 v[80:95], v[244:247], v[108:111], v[80:95]
	ds_read_b128 v[244:247], v227 offset:6720
	v_max3_f32 v96, v96, v40, v41
	v_max3_f32 v96, v96, v42, v43
	v_max3_f32 v96, v96, v44, v45
	v_max3_f32 v96, v96, v46, v47
	v_cmp_lt_f32_e32 vcc, 0x41000000, v96
	s_waitcnt lgkmcnt(5)
	v_mfma_f32_32x32x16_bf16 v[80:95], v[248:251], v[112:115], v[80:95]
	ds_read_b128 v[248:251], v227 offset:6752
	s_cbranch_vccz .LBB0_2719
	ds_bpermute_b32 v193, v186, v96
	s_waitcnt lgkmcnt(0)
	v_max_f32_e32 v193, v96, v193
	v_max_f32_e32 v193, 0, v193
	v_sub_f32_e32 v96, 0, v193
	v_exp_f32_e32 v96, v96
	s_nop 0
	v_mul_f32_e32 v192, v192, v96
	v_pk_mul_f32 v[30:31], v[30:31], v[96:97] op_sel_hi:[1,0]
	v_pk_mul_f32 v[28:29], v[28:29], v[96:97] op_sel_hi:[1,0]
	v_pk_mul_f32 v[26:27], v[26:27], v[96:97] op_sel_hi:[1,0]
	v_pk_mul_f32 v[24:25], v[24:25], v[96:97] op_sel_hi:[1,0]
	v_pk_mul_f32 v[22:23], v[22:23], v[96:97] op_sel_hi:[1,0]
	v_pk_mul_f32 v[20:21], v[20:21], v[96:97] op_sel_hi:[1,0]
	v_pk_mul_f32 v[18:19], v[18:19], v[96:97] op_sel_hi:[1,0]
	v_pk_mul_f32 v[16:17], v[16:17], v[96:97] op_sel_hi:[1,0]
	v_pk_mul_f32 v[14:15], v[14:15], v[96:97] op_sel_hi:[1,0]
	v_pk_mul_f32 v[12:13], v[12:13], v[96:97] op_sel_hi:[1,0]
	v_pk_mul_f32 v[10:11], v[10:11], v[96:97] op_sel_hi:[1,0]
	v_pk_mul_f32 v[8:9], v[8:9], v[96:97] op_sel_hi:[1,0]
	v_pk_mul_f32 v[6:7], v[6:7], v[96:97] op_sel_hi:[1,0]
	v_pk_mul_f32 v[4:5], v[4:5], v[96:97] op_sel_hi:[1,0]
	v_pk_mul_f32 v[2:3], v[2:3], v[96:97] op_sel_hi:[1,0]
	v_pk_mul_f32 v[0:1], v[0:1], v[96:97] op_sel_hi:[1,0]
	v_sub_f32_e32 v160, v160, v193
	v_sub_f32_e32 v161, v161, v193
	v_sub_f32_e32 v162, v162, v193
	v_sub_f32_e32 v163, v163, v193
	v_sub_f32_e32 v164, v164, v193
	v_sub_f32_e32 v165, v165, v193
	v_sub_f32_e32 v166, v166, v193
	v_sub_f32_e32 v167, v167, v193
	v_sub_f32_e32 v168, v168, v193
	v_sub_f32_e32 v169, v169, v193
	v_sub_f32_e32 v170, v170, v193
	v_sub_f32_e32 v171, v171, v193
	v_sub_f32_e32 v172, v172, v193
	v_sub_f32_e32 v173, v173, v193
	v_sub_f32_e32 v174, v174, v193
	v_sub_f32_e32 v175, v175, v193
	v_sub_f32_e32 v48, v48, v193
	v_sub_f32_e32 v49, v49, v193
	v_sub_f32_e32 v50, v50, v193
	v_sub_f32_e32 v51, v51, v193
	v_sub_f32_e32 v52, v52, v193
	v_sub_f32_e32 v53, v53, v193
	v_sub_f32_e32 v54, v54, v193
	v_sub_f32_e32 v55, v55, v193
	v_sub_f32_e32 v56, v56, v193
	v_sub_f32_e32 v57, v57, v193
	v_sub_f32_e32 v58, v58, v193
	v_sub_f32_e32 v59, v59, v193
	v_sub_f32_e32 v60, v60, v193
	v_sub_f32_e32 v61, v61, v193
	v_sub_f32_e32 v62, v62, v193
	v_sub_f32_e32 v63, v63, v193
	v_sub_f32_e32 v32, v32, v193
	v_sub_f32_e32 v33, v33, v193
	v_sub_f32_e32 v34, v34, v193
	v_sub_f32_e32 v35, v35, v193
	v_sub_f32_e32 v36, v36, v193
	v_sub_f32_e32 v37, v37, v193
	v_sub_f32_e32 v38, v38, v193
	v_sub_f32_e32 v39, v39, v193
	v_sub_f32_e32 v40, v40, v193
	v_sub_f32_e32 v41, v41, v193
	v_sub_f32_e32 v42, v42, v193
	v_sub_f32_e32 v43, v43, v193
	v_sub_f32_e32 v44, v44, v193
	v_sub_f32_e32 v45, v45, v193
	v_sub_f32_e32 v46, v46, v193
	v_sub_f32_e32 v47, v47, v193
	v_sub_f32_e32 v80, v80, v193
	v_sub_f32_e32 v81, v81, v193
	v_sub_f32_e32 v82, v82, v193
	v_sub_f32_e32 v83, v83, v193
	v_sub_f32_e32 v84, v84, v193
	v_sub_f32_e32 v85, v85, v193
	v_sub_f32_e32 v86, v86, v193
	v_sub_f32_e32 v87, v87, v193
	v_sub_f32_e32 v88, v88, v193
	v_sub_f32_e32 v89, v89, v193
	v_sub_f32_e32 v90, v90, v193
	v_sub_f32_e32 v91, v91, v193
	v_sub_f32_e32 v92, v92, v193
	v_sub_f32_e32 v93, v93, v193
	v_sub_f32_e32 v94, v94, v193
	v_sub_f32_e32 v95, v95, v193
.LBB0_2719:
	v_exp_f32_e32 v193, v48
	v_exp_f32_e32 v195, v49
	s_waitcnt lgkmcnt(5)
	v_mfma_f32_32x32x16_bf16 v[80:95], v[228:231], v[116:119], v[80:95]
	ds_read_b128 v[228:231], v227 offset:6784
	v_exp_f32_e32 v196, v50
	v_exp_f32_e32 v197, v51
	s_waitcnt lgkmcnt(5)
	v_mfma_f32_32x32x16_bf16 v[80:95], v[232:235], v[120:123], v[80:95]
	ds_read_b128 v[232:235], v227 offset:6816
	v_exp_f32_e32 v199, v52
	v_exp_f32_e32 v200, v53
	s_waitcnt lgkmcnt(5)
	v_mfma_f32_32x32x16_bf16 v[64:79], v[236:239], v[100:103], v[160:175]
	v_exp_f32_e32 v201, v54
	v_exp_f32_e32 v202, v55
	s_waitcnt lgkmcnt(4)
	v_mfma_f32_32x32x16_bf16 v[64:79], v[240:243], v[104:107], v[64:79]
	v_exp_f32_e32 v203, v56
	v_exp_f32_e32 v204, v57
	s_waitcnt lgkmcnt(3)
	v_mfma_f32_32x32x16_bf16 v[64:79], v[244:247], v[108:111], v[64:79]
	v_exp_f32_e32 v205, v58
	s_waitcnt lgkmcnt(2)
	v_mfma_f32_32x32x16_bf16 v[64:79], v[248:251], v[112:115], v[64:79]
	s_mul_i32 s20, s12, 0x2400
	v_exp_f32_e32 v206, v59
	v_exp_f32_e32 v211, v32
	v_mov_b32_e32 v32, v33
	s_waitcnt lgkmcnt(1)
	v_mfma_f32_32x32x16_bf16 v[64:79], v[228:231], v[116:119], v[64:79]
	v_lshlrev_b32_e32 v33, 1, v185
	v_lshlrev_b32_e32 v96, 1, v253
	v_exp_f32_e32 v207, v60
	s_waitcnt lgkmcnt(0)
	v_mfma_f32_32x32x16_bf16 v[64:79], v[232:235], v[120:123], v[64:79]
	v_add3_u32 v52, s20, v33, v96
	v_exp_f32_e32 v208, v61
	v_add_u32_e32 v58, 0xa800, v52
	v_exp_f32_e32 v209, v62
	v_add_u32_e32 v56, 0x9800, v52
	ds_read_b64 v[52:53], v58 offset:1536
	ds_read_b64 v[54:55], v58 offset:1552
	v_exp_f32_e32 v210, v63
	ds_read_b64 v[48:49], v56 offset:1024
	ds_read_b64 v[50:51], v56 offset:1040
	v_exp_f32_e32 v212, v32
	v_exp_f32_e32 v215, v36
	v_exp_f32_e32 v213, v34
	v_mov_b32_e32 v57, v35
	v_cvt_pk_bf16_f32 v32, v193, v195
	v_cvt_pk_bf16_f32 v33, v196, v197
	v_cvt_pk_bf16_f32 v34, v199, v200
	v_cvt_pk_bf16_f32 v35, v201, v202
	v_exp_f32_e32 v216, v37
	s_waitcnt lgkmcnt(2)
	v_mfma_f32_32x32x16_bf16 v[0:15], v[52:55], v[32:35], v[0:15]
	v_exp_f32_e32 v217, v38
	v_mov_b32_e32 v52, v39
	ds_read_b64 v[36:37], v58 offset:1568
	ds_read_b64 v[38:39], v58 offset:1584
	v_exp_f32_e32 v214, v57
	v_exp_f32_e32 v218, v52
	v_exp_f32_e32 v219, v40
	s_waitcnt lgkmcnt(2)
	v_mfma_f32_32x32x16_bf16 v[16:31], v[48:51], v[32:35], v[16:31]
	ds_read_b64 v[48:49], v56 offset:1056
	ds_read_b64 v[50:51], v56 offset:1072
	v_cvt_pk_bf16_f32 v32, v203, v204
	v_cvt_pk_bf16_f32 v33, v205, v206
	v_cvt_pk_bf16_f32 v34, v207, v208
	v_cvt_pk_bf16_f32 v35, v209, v210
	v_exp_f32_e32 v220, v41
	s_waitcnt lgkmcnt(2)
	v_mfma_f32_32x32x16_bf16 v[0:15], v[36:39], v[32:35], v[0:15]
	ds_read_b64 v[36:37], v58 offset:1600
	ds_read_b64 v[38:39], v58 offset:1616
	v_exp_f32_e32 v221, v42
	v_exp_f32_e32 v222, v43
	v_exp_f32_e32 v223, v44
	s_waitcnt lgkmcnt(2)
	v_mfma_f32_32x32x16_bf16 v[16:31], v[48:51], v[32:35], v[16:31]
	ds_read_b64 v[48:49], v56 offset:1088
	ds_read_b64 v[50:51], v56 offset:1104
	v_cvt_pk_bf16_f32 v32, v211, v212
	v_cvt_pk_bf16_f32 v33, v213, v214
	v_cvt_pk_bf16_f32 v34, v215, v216
	v_cvt_pk_bf16_f32 v35, v217, v218
	v_exp_f32_e32 v224, v45
	ds_read_b64 v[40:41], v56 offset:1120
	ds_read_b64 v[42:43], v56 offset:1136
	s_waitcnt lgkmcnt(4)
	v_mfma_f32_32x32x16_bf16 v[0:15], v[36:39], v[32:35], v[0:15]
	ds_read_b64 v[36:37], v58 offset:1632
	ds_read_b64 v[38:39], v58 offset:1648
	v_exp_f32_e32 v225, v46
	s_add_i32 s4, s16, -4
	s_cmp_ge_u32 s4, s9
	s_waitcnt lgkmcnt(0)
	s_barrier
	v_mfma_f32_32x32x16_bf16 v[16:31], v[48:51], v[32:35], v[16:31]
	v_exp_f32_e32 v226, v47
	v_cvt_pk_bf16_f32 v32, v219, v220
	v_cvt_pk_bf16_f32 v33, v221, v222
	v_cvt_pk_bf16_f32 v34, v223, v224
	v_cvt_pk_bf16_f32 v35, v225, v226
	s_nop 1
	v_mfma_f32_32x32x16_bf16 v[16:31], v[40:43], v[32:35], v[16:31]
	v_mfma_f32_32x32x16_bf16 v[0:15], v[36:39], v[32:35], v[0:15]
	s_cbranch_scc1 .LBB0_2726
	s_mul_i32 s21, s12, 0x3400
	v_add3_u32 v32, s21, v190, v198
	s_waitcnt vmcnt(1)
	ds_write_b128 v32, v[128:131]
	s_and_saveexec_b64 s[4:5], s[10:11]
	v_lshlrev_b32_e32 v32, 1, v180
	v_lshlrev_b32_e32 v33, 1, v142
	v_add3_u32 v32, s21, v32, v33
	ds_write_b128 v32, v[124:127]
	s_or_b64 exec, exec, s[4:5]
	v_lshlrev_b32_e32 v32, 1, v182
	v_add3_u32 v32, s20, v32, v158
	s_cmp_ge_u32 s16, s8
	s_waitcnt vmcnt(0)
	ds_write_b128 v32, v[132:135] offset:39936
	s_cbranch_scc1 .LBB0_2726
	v_lshl_add_u64 v[32:33], s[90:91], 0, v[178:179]
	v_add_co_u32_e32 v32, vcc, 0x159c0000, v32
	s_nop 1
	v_addc_co_u32_e32 v33, vcc, 0, v33, vcc
	global_load_dwordx4 v[128:131], v[32:33], off
	s_and_saveexec_b64 s[4:5], s[10:11]
	s_cbranch_execz .LBB0_2725
	v_lshl_add_u64 v[32:33], s[90:91], 0, v[176:177]
	v_add_co_u32_e32 v32, vcc, 0x159c0000, v32
	s_nop 1
	v_addc_co_u32_e32 v33, vcc, 0, v33, vcc
	global_load_dwordx4 v[124:127], v[32:33], off

.LBB0_2728:
	v_add_f32_e32 v193, 0, v193
	v_add_f32_e32 v195, 0, v195
	v_add_f32_e32 v193, v196, v193
	v_add_f32_e32 v195, v197, v195
	s_waitcnt lgkmcnt(5)
	v_mfma_f32_32x32x16_bf16 v[48:63], v[236:239], v[100:103], v[160:175]
	ds_read_b128 v[236:239], v198 offset:6656
	v_add_f32_e32 v193, v199, v193
	v_add_f32_e32 v195, v200, v195
	v_add_f32_e32 v193, v201, v193
	v_add_f32_e32 v195, v202, v195
	s_waitcnt lgkmcnt(5)
	v_mfma_f32_32x32x16_bf16 v[48:63], v[240:243], v[104:107], v[48:63]
	ds_read_b128 v[240:243], v198 offset:6688
	v_add_f32_e32 v193, v203, v193
	v_add_f32_e32 v195, v204, v195
	v_add_f32_e32 v193, v205, v193
	v_add_f32_e32 v195, v206, v195
	s_waitcnt lgkmcnt(5)
	v_mfma_f32_32x32x16_bf16 v[48:63], v[244:247], v[108:111], v[48:63]
	ds_read_b128 v[244:247], v198 offset:6720
	v_add_f32_e32 v193, v207, v193
	v_add_f32_e32 v195, v208, v195
	v_add_f32_e32 v193, v209, v193
	v_add_f32_e32 v195, v210, v195
	s_waitcnt lgkmcnt(5)
	v_mfma_f32_32x32x16_bf16 v[48:63], v[248:251], v[112:115], v[48:63]
	ds_read_b128 v[248:251], v198 offset:6752
	v_add_f32_e32 v193, v211, v193
	v_add_f32_e32 v195, v212, v195
	v_add_f32_e32 v193, v213, v193
	v_add_f32_e32 v195, v214, v195
	s_waitcnt lgkmcnt(5)
	v_mfma_f32_32x32x16_bf16 v[48:63], v[228:231], v[116:119], v[48:63]
	ds_read_b128 v[228:231], v198 offset:6784
	v_add_f32_e32 v193, v215, v193
	v_add_f32_e32 v195, v216, v195
	v_add_f32_e32 v193, v217, v193
	v_add_f32_e32 v195, v218, v195
	s_waitcnt lgkmcnt(5)
	v_mfma_f32_32x32x16_bf16 v[48:63], v[232:235], v[120:123], v[48:63]
	ds_read_b128 v[232:235], v198 offset:6816
	v_add_f32_e32 v193, v219, v193
	v_add_f32_e32 v195, v220, v195
	v_add_f32_e32 v193, v221, v193
	v_add_f32_e32 v195, v222, v195
	s_waitcnt lgkmcnt(5)
	v_mfma_f32_32x32x16_bf16 v[32:47], v[236:239], v[100:103], v[160:175]
	v_add_f32_e32 v193, v223, v193
	v_add_f32_e32 v195, v224, v195
	v_add_f32_e32 v193, v225, v193
	v_add_f32_e32 v195, v226, v195
	s_waitcnt lgkmcnt(4)
	v_mfma_f32_32x32x16_bf16 v[32:47], v[240:243], v[104:107], v[32:47]
	v_add_f32_e32 v193, v195, v193
	v_add_f32_e32 v192, v192, v193
	v_max_f32_e32 v193, v81, v81
	v_max_f32_e32 v195, v80, v80
	s_waitcnt lgkmcnt(3)
	v_mfma_f32_32x32x16_bf16 v[32:47], v[244:247], v[108:111], v[32:47]
	v_max_f32_e32 v193, v195, v193
	v_max3_f32 v193, v193, v82, v83
	v_max3_f32 v193, v193, v84, v85
	v_max3_f32 v193, v193, v86, v87
	s_waitcnt lgkmcnt(2)
	v_mfma_f32_32x32x16_bf16 v[32:47], v[248:251], v[112:115], v[32:47]
	v_max3_f32 v193, v193, v88, v89
	v_max3_f32 v193, v193, v90, v91
	v_max3_f32 v193, v193, v92, v93
	v_max3_f32 v193, v193, v94, v95
	s_waitcnt lgkmcnt(1)
	v_mfma_f32_32x32x16_bf16 v[32:47], v[228:231], v[116:119], v[32:47]
	v_max3_f32 v193, v193, v64, v65
	v_max3_f32 v193, v193, v66, v67
	v_max3_f32 v193, v193, v68, v69
	v_max3_f32 v193, v193, v70, v71
	s_waitcnt lgkmcnt(0)
	v_mfma_f32_32x32x16_bf16 v[32:47], v[232:235], v[120:123], v[32:47]
	v_max3_f32 v193, v193, v72, v73
	v_max3_f32 v193, v193, v74, v75
	v_max3_f32 v193, v193, v76, v77
	v_max3_f32 v193, v193, v78, v79
	v_cmp_lt_f32_e32 vcc, 0x41000000, v193
	s_cbranch_vccz .LBB0_2730
	ds_bpermute_b32 v195, v186, v193
	s_waitcnt lgkmcnt(0)
	v_max_f32_e32 v195, v193, v195
	v_max_f32_e32 v195, 0, v195
	v_sub_f32_e32 v196, 0, v195
	v_exp_f32_e32 v196, v196
	s_nop 0
	v_mul_f32_e32 v192, v192, v196
	v_pk_mul_f32 v[30:31], v[30:31], v[196:197] op_sel_hi:[1,0]
	v_pk_mul_f32 v[28:29], v[28:29], v[196:197] op_sel_hi:[1,0]
	v_pk_mul_f32 v[26:27], v[26:27], v[196:197] op_sel_hi:[1,0]
	v_pk_mul_f32 v[24:25], v[24:25], v[196:197] op_sel_hi:[1,0]
	v_pk_mul_f32 v[22:23], v[22:23], v[196:197] op_sel_hi:[1,0]
	v_pk_mul_f32 v[20:21], v[20:21], v[196:197] op_sel_hi:[1,0]
	v_pk_mul_f32 v[18:19], v[18:19], v[196:197] op_sel_hi:[1,0]
	v_pk_mul_f32 v[16:17], v[16:17], v[196:197] op_sel_hi:[1,0]
	v_pk_mul_f32 v[14:15], v[14:15], v[196:197] op_sel_hi:[1,0]
	v_pk_mul_f32 v[12:13], v[12:13], v[196:197] op_sel_hi:[1,0]
	v_pk_mul_f32 v[10:11], v[10:11], v[196:197] op_sel_hi:[1,0]
	v_pk_mul_f32 v[8:9], v[8:9], v[196:197] op_sel_hi:[1,0]
	v_pk_mul_f32 v[6:7], v[6:7], v[196:197] op_sel_hi:[1,0]
	v_pk_mul_f32 v[4:5], v[4:5], v[196:197] op_sel_hi:[1,0]
	v_pk_mul_f32 v[2:3], v[2:3], v[196:197] op_sel_hi:[1,0]
	v_pk_mul_f32 v[0:1], v[0:1], v[196:197] op_sel_hi:[1,0]
	v_sub_f32_e32 v160, v160, v195
	v_sub_f32_e32 v161, v161, v195
	v_sub_f32_e32 v162, v162, v195
	v_sub_f32_e32 v163, v163, v195
	v_sub_f32_e32 v164, v164, v195
	v_sub_f32_e32 v165, v165, v195
	v_sub_f32_e32 v166, v166, v195
	v_sub_f32_e32 v167, v167, v195
	v_sub_f32_e32 v168, v168, v195
	v_sub_f32_e32 v169, v169, v195
	v_sub_f32_e32 v170, v170, v195
	v_sub_f32_e32 v171, v171, v195
	v_sub_f32_e32 v172, v172, v195
	v_sub_f32_e32 v173, v173, v195
	v_sub_f32_e32 v174, v174, v195
	v_sub_f32_e32 v175, v175, v195
	v_sub_f32_e32 v80, v80, v195
	v_sub_f32_e32 v81, v81, v195
	v_sub_f32_e32 v82, v82, v195
	v_sub_f32_e32 v83, v83, v195
	v_sub_f32_e32 v84, v84, v195
	v_sub_f32_e32 v85, v85, v195
	v_sub_f32_e32 v86, v86, v195
	v_sub_f32_e32 v87, v87, v195
	v_sub_f32_e32 v88, v88, v195
	v_sub_f32_e32 v89, v89, v195
	v_sub_f32_e32 v90, v90, v195
	v_sub_f32_e32 v91, v91, v195
	v_sub_f32_e32 v92, v92, v195
	v_sub_f32_e32 v93, v93, v195
	v_sub_f32_e32 v94, v94, v195
	v_sub_f32_e32 v95, v95, v195
	v_sub_f32_e32 v64, v64, v195
	v_sub_f32_e32 v65, v65, v195
	v_sub_f32_e32 v66, v66, v195
	v_sub_f32_e32 v67, v67, v195
	v_sub_f32_e32 v68, v68, v195
	v_sub_f32_e32 v69, v69, v195
	v_sub_f32_e32 v70, v70, v195
	v_sub_f32_e32 v71, v71, v195
	v_sub_f32_e32 v72, v72, v195
	v_sub_f32_e32 v73, v73, v195
	v_sub_f32_e32 v74, v74, v195
	v_sub_f32_e32 v75, v75, v195
	v_sub_f32_e32 v76, v76, v195
	v_sub_f32_e32 v77, v77, v195
	v_sub_f32_e32 v78, v78, v195
	v_sub_f32_e32 v79, v79, v195
	v_sub_f32_e32 v48, v48, v195
	v_sub_f32_e32 v49, v49, v195
	v_sub_f32_e32 v50, v50, v195
	v_sub_f32_e32 v51, v51, v195
	v_sub_f32_e32 v52, v52, v195
	v_sub_f32_e32 v53, v53, v195
	v_sub_f32_e32 v54, v54, v195
	v_sub_f32_e32 v55, v55, v195
	v_sub_f32_e32 v56, v56, v195
	v_sub_f32_e32 v57, v57, v195
	v_sub_f32_e32 v58, v58, v195
	v_sub_f32_e32 v59, v59, v195
	v_sub_f32_e32 v60, v60, v195
	v_sub_f32_e32 v61, v61, v195
	v_sub_f32_e32 v62, v62, v195
	v_sub_f32_e32 v63, v63, v195
	v_sub_f32_e32 v32, v32, v195
	v_sub_f32_e32 v33, v33, v195
	v_sub_f32_e32 v34, v34, v195
	v_sub_f32_e32 v35, v35, v195
	v_sub_f32_e32 v36, v36, v195
	v_sub_f32_e32 v37, v37, v195
	v_sub_f32_e32 v38, v38, v195
	v_sub_f32_e32 v39, v39, v195
	v_sub_f32_e32 v40, v40, v195
	v_sub_f32_e32 v41, v41, v195
	v_sub_f32_e32 v42, v42, v195
	v_sub_f32_e32 v43, v43, v195
	v_sub_f32_e32 v44, v44, v195
	v_sub_f32_e32 v45, v45, v195
	v_sub_f32_e32 v46, v46, v195
	v_sub_f32_e32 v47, v47, v195
.LBB0_2730:
	v_exp_f32_e32 v80, v80
	v_exp_f32_e32 v81, v81
	v_exp_f32_e32 v82, v82
	v_exp_f32_e32 v83, v83
	v_exp_f32_e32 v201, v84
	v_exp_f32_e32 v202, v85
	v_mov_b32_e32 v84, v86
	v_mov_b32_e32 v86, v88
	v_mov_b32_e32 v88, v90
	v_mov_b32_e32 v90, v92
	v_mov_b32_e32 v92, v94
	v_exp_f32_e32 v94, v64
	v_add_f32_e32 v193, 0, v80
	v_exp_f32_e32 v203, v84
	v_mov_b32_e32 v84, v87
	v_mov_b32_e32 v87, v89
	v_mov_b32_e32 v89, v91
	v_mov_b32_e32 v91, v93
	v_mov_b32_e32 v93, v95
	v_exp_f32_e32 v95, v65
	s_mul_i32 s4, s13, 0x2400
	v_add_f32_e32 v195, 0, v81
	v_add_f32_e32 v193, v82, v193
	v_exp_f32_e32 v196, v66
	v_add_f32_e32 v195, v83, v195
	v_exp_f32_e32 v204, v84
	v_add_f32_e32 v84, v201, v193
	v_exp_f32_e32 v197, v67
	v_add_u32_e32 v193, s4, v159
	v_add_f32_e32 v85, v202, v195
	v_exp_f32_e32 v198, v68
	v_add_u32_e32 v195, 0x9800, v193
	v_exp_f32_e32 v199, v69
	ds_read_b64 v[64:65], v195 offset:1024
	ds_read_b64 v[66:67], v195 offset:1040
	v_add_u32_e32 v193, 0xa800, v193
	v_exp_f32_e32 v200, v70
	v_mov_b32_e32 v205, v71
	v_cvt_pk_bf16_f32 v68, v80, v81
	v_cvt_pk_bf16_f32 v69, v82, v83
	v_cvt_pk_bf16_f32 v70, v201, v202
	v_cvt_pk_bf16_f32 v71, v203, v204
	ds_read_b64 v[80:81], v193 offset:1536
	ds_read_b64 v[82:83], v193 offset:1552
	v_add_f32_e32 v84, v203, v84
	s_waitcnt lgkmcnt(2)
	v_mfma_f32_32x32x16_bf16 v[16:31], v[64:67], v[68:71], v[16:31]
	v_exp_f32_e32 v202, v72
	v_exp_f32_e32 v203, v73
	ds_read_b64 v[64:65], v195 offset:1056
	ds_read_b64 v[66:67], v195 offset:1072
	v_exp_f32_e32 v86, v86
	v_exp_f32_e32 v87, v87
	v_exp_f32_e32 v88, v88
	v_exp_f32_e32 v89, v89
	v_exp_f32_e32 v90, v90
	v_exp_f32_e32 v91, v91
	v_exp_f32_e32 v92, v92
	v_exp_f32_e32 v93, v93
	s_waitcnt lgkmcnt(2)
	v_mfma_f32_32x32x16_bf16 v[0:15], v[80:83], v[68:71], v[0:15]
	v_exp_f32_e32 v80, v74
	v_mov_b32_e32 v81, v75
	ds_read_b64 v[72:73], v193 offset:1568
	ds_read_b64 v[74:75], v193 offset:1584
	v_cvt_pk_bf16_f32 v68, v86, v87
	v_cvt_pk_bf16_f32 v69, v88, v89
	v_cvt_pk_bf16_f32 v70, v90, v91
	v_cvt_pk_bf16_f32 v71, v92, v93
	v_exp_f32_e32 v201, v205
	v_add_f32_e32 v85, v204, v85
	s_waitcnt lgkmcnt(2)
	v_mfma_f32_32x32x16_bf16 v[16:31], v[64:67], v[68:71], v[16:31]
	v_exp_f32_e32 v76, v76
	v_exp_f32_e32 v77, v77
	ds_read_b64 v[64:65], v195 offset:1088
	ds_read_b64 v[66:67], v195 offset:1104
	s_waitcnt lgkmcnt(2)
	v_mfma_f32_32x32x16_bf16 v[0:15], v[72:75], v[68:71], v[0:15]
	ds_read_b64 v[72:73], v193 offset:1600
	ds_read_b64 v[74:75], v193 offset:1616
	v_cvt_pk_bf16_f32 v68, v94, v95
	v_cvt_pk_bf16_f32 v69, v196, v197
	v_cvt_pk_bf16_f32 v70, v198, v199
	v_cvt_pk_bf16_f32 v71, v200, v201
	v_exp_f32_e32 v81, v81
	v_exp_f32_e32 v78, v78
	s_waitcnt lgkmcnt(2)
	v_mfma_f32_32x32x16_bf16 v[16:31], v[64:67], v[68:71], v[16:31]
	v_add_f32_e64 v64, v86, v84
	v_add_f32_e64 v65, v87, v85
	v_exp_f32_e32 v79, v79
	v_pk_add_f32 v[64:65], v[88:89], v[64:65]
	s_add_i32 s16, s16, 2
	v_pk_add_f32 v[64:65], v[90:91], v[64:65]
	v_lshl_add_u64 v[98:99], v[98:99], 0, s[40:41]
	v_pk_add_f32 v[64:65], v[92:93], v[64:65]
	s_waitcnt lgkmcnt(0)
	v_mfma_f32_32x32x16_bf16 v[0:15], v[72:75], v[68:71], v[0:15]
	v_add_f32_e64 v82, v94, v64
	v_add_f32_e64 v83, v95, v65
	ds_read_b64 v[64:65], v195 offset:1120
	ds_read_b64 v[66:67], v195 offset:1136
	ds_read_b64 v[72:73], v193 offset:1632
	ds_read_b64 v[74:75], v193 offset:1648
	v_add_f32_e64 v68, v196, v82
	v_add_f32_e64 v69, v197, v83
	v_cvt_pk_bf16_f32 v70, v76, v77
	v_pk_add_f32 v[82:83], v[198:199], v[68:69]
	v_cvt_pk_bf16_f32 v68, v202, v203
	v_cvt_pk_bf16_f32 v69, v80, v81
	v_cvt_pk_bf16_f32 v71, v78, v79
	v_lshl_add_u64 v[176:177], v[176:177], 0, s[42:43]
	s_cmp_ge_u32 s18, s8
	s_waitcnt lgkmcnt(2)
	v_mfma_f32_32x32x16_bf16 v[16:31], v[64:67], v[68:71], v[16:31]
	v_add_f32_e64 v64, v200, v82
	v_add_f32_e64 v65, v201, v83
	v_lshl_add_u64 v[178:179], v[178:179], 0, s[42:43]
	v_add_f32_e64 v64, v202, v64
	v_add_f32_e64 v65, v203, v65
	v_pk_add_f32 v[64:65], v[80:81], v[64:65]
	s_nop 0
	v_pk_add_f32 v[64:65], v[76:77], v[64:65]
	s_waitcnt lgkmcnt(0)
	v_mfma_f32_32x32x16_bf16 v[0:15], v[72:75], v[68:71], v[0:15]
	v_add_f32_e64 v64, v78, v64
	v_add_f32_e64 v65, v79, v65
	v_add_f32_e32 v64, v64, v65
	v_add_f32_e32 v192, v192, v64
	s_cbranch_scc1 .LBB0_2693
	s_mov_b32 s4, s13
	s_mov_b32 s13, s12
	s_mov_b32 s12, s17
	s_branch .LBB0_2710
